# loop-edge rotation (lever 9): attention steady loop's slot rotation / counter / pointer advance / exit test computed in front of the step-closing barrier instead of behind it
# baseline (speedup 1.0000x reference)
.LBB0_149:
	ds_read_b128 v[32:35], v180
	ds_read_b128 v[84:87], v180 offset:32
	ds_read_b128 v[136:139], v180 offset:128
	ds_read_b128 v[36:39], v180 offset:160
	ds_read_b128 v[88:91], v180 offset:64
	ds_read_b128 v[92:95], v180 offset:96
	ds_read_b128 v[40:43], v180 offset:192
	ds_read_b128 v[44:47], v180 offset:224
	s_waitcnt lgkmcnt(14)
	v_mfma_f32_32x32x16_bf16 v[16:31], v[124:127], v[164:167], v[16:31]
	v_exp_f32_e32 v64, v64
	v_exp_f32_e32 v65, v65
	v_exp_f32_e32 v66, v66
	v_exp_f32_e32 v67, v67
	s_waitcnt lgkmcnt(7)
	v_pk_add_f32 v[80:81], v[32:33], v[204:205] op_sel_hi:[1,0] neg_lo:[0,1] neg_hi:[0,1]
	v_pk_add_f32 v[82:83], v[34:35], v[204:205] op_sel_hi:[1,0] neg_lo:[0,1] neg_hi:[0,1]
	s_waitcnt lgkmcnt(2)
	v_mfma_f32_32x32x16_bf16 v[0:15], v[124:127], v[160:163], v[0:15]
	v_exp_f32_e32 v68, v68
	v_exp_f32_e32 v69, v69
	v_exp_f32_e32 v70, v70
	v_exp_f32_e32 v71, v71
	v_pk_add_f32 v[84:85], v[84:85], v[204:205] op_sel_hi:[1,0] neg_lo:[0,1] neg_hi:[0,1]
	v_pk_add_f32 v[86:87], v[86:87], v[204:205] op_sel_hi:[1,0] neg_lo:[0,1] neg_hi:[0,1]
	v_add_u32_e32 v124, s28, v220
	ds_read_b128 v[168:171], v124
	ds_read_b128 v[128:131], v124 offset:512
	v_mfma_f32_32x32x16_bf16 v[16:31], v[120:123], v[152:155], v[16:31]
	v_exp_f32_e32 v72, v72
	v_exp_f32_e32 v73, v73
	v_exp_f32_e32 v74, v74
	v_exp_f32_e32 v75, v75
	v_pk_add_f32 v[88:89], v[88:89], v[204:205] op_sel_hi:[1,0] neg_lo:[0,1] neg_hi:[0,1]
	v_pk_add_f32 v[90:91], v[90:91], v[204:205] op_sel_hi:[1,0] neg_lo:[0,1] neg_hi:[0,1]
	ds_read_b128 v[164:167], v124 offset:2048
	ds_read_b128 v[152:155], v124 offset:2560
	v_mfma_f32_32x32x16_bf16 v[0:15], v[120:123], v[148:151], v[0:15]
	v_exp_f32_e32 v76, v76
	v_exp_f32_e32 v77, v77
	v_exp_f32_e32 v78, v78
	v_exp_f32_e32 v79, v79
	v_pk_add_f32 v[92:93], v[92:93], v[204:205] op_sel_hi:[1,0] neg_lo:[0,1] neg_hi:[0,1]
	v_pk_add_f32 v[94:95], v[94:95], v[204:205] op_sel_hi:[1,0] neg_lo:[0,1] neg_hi:[0,1]
	ds_read_b128 v[160:163], v124 offset:4096
	ds_read_b128 v[148:151], v124 offset:4608
	v_mfma_f32_32x32x16_bf16 v[16:31], v[112:115], v[156:159], v[16:31]
	v_exp_f32_e32 v48, v48
	v_exp_f32_e32 v49, v49
	v_exp_f32_e32 v50, v50
	v_exp_f32_e32 v51, v51
	v_pk_add_f32 v[32:33], v[136:137], v[204:205] op_sel_hi:[1,0] neg_lo:[0,1] neg_hi:[0,1]
	v_pk_add_f32 v[34:35], v[138:139], v[204:205] op_sel_hi:[1,0] neg_lo:[0,1] neg_hi:[0,1]
	s_waitcnt lgkmcnt(6)
	ds_read_b128 v[156:159], v124 offset:6144
	ds_read_b128 v[136:139], v124 offset:6656
	v_mfma_f32_32x32x16_bf16 v[0:15], v[112:115], v[144:147], v[0:15]
	v_exp_f32_e32 v52, v52
	v_exp_f32_e32 v53, v53
	v_exp_f32_e32 v54, v54
	v_exp_f32_e32 v55, v55
	v_pk_add_f32 v[36:37], v[36:37], v[204:205] op_sel_hi:[1,0] neg_lo:[0,1] neg_hi:[0,1]
	v_pk_add_f32 v[38:39], v[38:39], v[204:205] op_sel_hi:[1,0] neg_lo:[0,1] neg_hi:[0,1]
	v_mfma_f32_32x32x16_bf16 v[16:31], v[104:107], v[140:143], v[16:31]
	v_exp_f32_e32 v56, v56
	v_exp_f32_e32 v57, v57
	v_exp_f32_e32 v58, v58
	v_exp_f32_e32 v59, v59
	v_pk_add_f32 v[40:41], v[40:41], v[204:205] op_sel_hi:[1,0] neg_lo:[0,1] neg_hi:[0,1]
	v_pk_add_f32 v[42:43], v[42:43], v[204:205] op_sel_hi:[1,0] neg_lo:[0,1] neg_hi:[0,1]
	v_mfma_f32_32x32x16_bf16 v[0:15], v[104:107], v[132:135], v[0:15]
	v_exp_f32_e32 v60, v60
	v_exp_f32_e32 v61, v61
	v_exp_f32_e32 v62, v62
	v_exp_f32_e32 v63, v63
	v_pk_add_f32 v[44:45], v[44:45], v[204:205] op_sel_hi:[1,0] neg_lo:[0,1] neg_hi:[0,1]
	v_pk_add_f32 v[46:47], v[46:47], v[204:205] op_sel_hi:[1,0] neg_lo:[0,1] neg_hi:[0,1]
	s_add_i32 s100, s28, 0x2000
	s_cmpk_lg_i32 s28, 0x4000
	s_cselect_b32 s22, s100, 0
	s_waitcnt vmcnt(2) lgkmcnt(0)
	s_barrier
	s_andn2_b64 vcc, exec, s[6:7]
	s_cbranch_vccnz .LBB0_151
	s_waitcnt lgkmcnt(0)
	ds_read_b128 v[132:135], v216 offset:49248
	ds_read_b128 v[140:143], v216 offset:49216
	ds_read_b128 v[144:147], v216 offset:49184
	ds_read_b128 v[172:175], v216 offset:49152
	s_waitcnt lgkmcnt(3)
	v_pk_mul_f32 v[30:31], v[30:31], v[134:135]
	s_waitcnt lgkmcnt(2)
	v_pk_mul_f32 v[26:27], v[26:27], v[142:143]
	s_waitcnt lgkmcnt(1)
	v_pk_mul_f32 v[22:23], v[22:23], v[146:147]
	s_waitcnt lgkmcnt(0)
	v_pk_mul_f32 v[18:19], v[18:19], v[174:175]
	v_pk_mul_f32 v[28:29], v[28:29], v[132:133]
	v_pk_mul_f32 v[24:25], v[24:25], v[140:141]
	v_pk_mul_f32 v[20:21], v[20:21], v[144:145]
	v_pk_mul_f32 v[16:17], v[16:17], v[172:173]
	v_pk_mul_f32 v[14:15], v[14:15], v[134:135]
	v_pk_mul_f32 v[10:11], v[10:11], v[142:143]
	v_pk_mul_f32 v[6:7], v[6:7], v[146:147]
	v_pk_mul_f32 v[2:3], v[2:3], v[174:175]
	v_pk_mul_f32 v[12:13], v[12:13], v[132:133]
	v_pk_mul_f32 v[8:9], v[8:9], v[140:141]
	v_pk_mul_f32 v[4:5], v[4:5], v[144:145]
	v_pk_mul_f32 v[0:1], v[0:1], v[172:173]
.LBB0_151:
	v_add_u32_e32 v182, s41, v221
	ds_read_b64_tr_b16 v[144:145], v182 offset:24576
	ds_read_b64_tr_b16 v[146:147], v182 offset:25088
	v_mfma_f32_32x32x16_bf16 v[80:95], v[168:171], v[116:119], v[80:95]
	v_add_f32_e32 v104, v64, v65
	v_add_f32_e32 v104, v66, v104
	v_add_f32_e32 v104, v67, v104
	v_add_f32_e32 v104, v68, v104
	v_add_f32_e32 v104, v69, v104
	v_cvt_pk_bf16_f32 v124, v64, v65
	v_cvt_pk_bf16_f32 v125, v66, v67
	ds_read_b64_tr_b16 v[140:141], v182 offset:28672
	ds_read_b64_tr_b16 v[142:143], v182 offset:29184
	v_mfma_f32_32x32x16_bf16 v[32:47], v[128:131], v[116:119], v[32:47]
	v_add_f32_e32 v64, v70, v104
	v_add_f32_e32 v64, v71, v64
	v_add_f32_e32 v64, v72, v64
	v_add_f32_e32 v64, v73, v64
	v_cvt_pk_bf16_f32 v126, v68, v69
	v_cvt_pk_bf16_f32 v127, v70, v71
	ds_read_b64_tr_b16 v[132:133], v182 offset:25600
	ds_read_b64_tr_b16 v[134:135], v182 offset:26112
	v_mfma_f32_32x32x16_bf16 v[80:95], v[164:167], v[108:111], v[80:95]
	v_add_f32_e32 v64, v74, v64
	v_add_f32_e32 v64, v75, v64
	v_add_f32_e32 v64, v76, v64
	v_add_f32_e32 v64, v77, v64
	v_cvt_pk_bf16_f32 v120, v72, v73
	v_cvt_pk_bf16_f32 v121, v74, v75
	ds_read_b64_tr_b16 v[128:129], v182 offset:29696
	ds_read_b64_tr_b16 v[130:131], v182 offset:30208
	v_mfma_f32_32x32x16_bf16 v[32:47], v[152:155], v[108:111], v[32:47]
	v_add_f32_e32 v64, v78, v64
	v_add_f32_e32 v64, v79, v64
	v_add_f32_e32 v64, v48, v64
	v_add_f32_e32 v64, v49, v64
	v_cvt_pk_bf16_f32 v122, v76, v77
	v_cvt_pk_bf16_f32 v123, v78, v79
	ds_read_b64_tr_b16 v[172:173], v182 offset:26624
	ds_read_b64_tr_b16 v[174:175], v182 offset:27136
	v_mfma_f32_32x32x16_bf16 v[80:95], v[160:163], v[100:103], v[80:95]
	v_add_f32_e32 v64, v50, v64
	v_add_f32_e32 v64, v51, v64
	v_add_f32_e32 v64, v52, v64
	v_add_f32_e32 v64, v53, v64
	v_cvt_pk_bf16_f32 v112, v48, v49
	v_cvt_pk_bf16_f32 v113, v50, v51
	ds_read_b64_tr_b16 v[168:169], v182 offset:30720
	ds_read_b64_tr_b16 v[170:171], v182 offset:31232
	v_mfma_f32_32x32x16_bf16 v[32:47], v[148:151], v[100:103], v[32:47]
	v_add_f32_e32 v48, v54, v64
	v_add_f32_e32 v48, v55, v48
	v_add_f32_e32 v48, v56, v48
	v_add_f32_e32 v48, v57, v48
	v_cvt_pk_bf16_f32 v114, v52, v53
	v_cvt_pk_bf16_f32 v115, v54, v55
	ds_read_b64_tr_b16 v[164:165], v182 offset:27648
	ds_read_b64_tr_b16 v[166:167], v182 offset:28160
	v_mfma_f32_32x32x16_bf16 v[80:95], v[156:159], v[96:99], v[80:95]
	v_add_f32_e32 v48, v58, v48
	v_add_f32_e32 v48, v59, v48
	v_add_f32_e32 v48, v60, v48
	v_add_f32_e32 v48, v61, v48
	v_cvt_pk_bf16_f32 v104, v56, v57
	v_cvt_pk_bf16_f32 v105, v58, v59
	ds_read_b64_tr_b16 v[160:161], v182 offset:31744
	ds_read_b64_tr_b16 v[162:163], v182 offset:32256
	v_mfma_f32_32x32x16_bf16 v[32:47], v[136:139], v[96:99], v[32:47]
	v_add_f32_e32 v48, v62, v48
	v_add_f32_e32 v48, v63, v48
	v_add_f32_e32 v48, 0, v48
	v_cvt_pk_bf16_f32 v106, v60, v61
	v_cvt_pk_bf16_f32 v107, v62, v63
	v_max_f32_e32 v49, v80, v81
	s_nop 3
	v_max3_f32 v50, v82, v83, v33
	v_max3_f32 v49, v49, v32, v34
	v_max3_f32 v49, v49, v35, v84
	v_max3_f32 v50, v50, v86, v87
	v_max3_f32 v49, v49, v85, v36
	v_max3_f32 v50, v50, v38, v39
	v_max3_f32 v49, v49, v37, v88
	v_max3_f32 v50, v50, v90, v91
	v_max3_f32 v49, v49, v89, v40
	v_max3_f32 v50, v50, v42, v43
	v_max3_f32 v49, v49, v41, v92
	v_max3_f32 v50, v50, v94, v95
	v_max3_f32 v49, v49, v93, v44
	v_max3_f32 v50, v50, v46, v47
	v_add_f32_e32 v222, v181, v48
	v_max3_f32 v48, v49, v45, v50
	v_mov_b32_e32 v49, v48
	s_nop 1
	v_permlane32_swap_b32_e32 v48, v49
	v_max_f32_e32 v49, v49, v49
	v_max_f32_e32 v48, v48, v48
	s_add_i32 s6, s28, s18
	s_mov_b32 m0, s6
	s_nop 0
	global_load_lds_dwordx4 v[178:179], off
	v_max_f32_e32 v48, v48, v49
	s_add_i32 s6, s22, s19
	s_mov_b32 m0, s6
	s_nop 0
	global_load_lds_dwordx4 v[176:177], off
	v_cmp_lt_f32_e32 vcc, s47, v48
	s_cmp_lg_u64 vcc, 0
	s_cselect_b64 s[6:7], -1, 0
	s_cbranch_vccnz .LBB0_159
.LBB0_152:
	ds_read_b128 v[48:51], v180 offset:256
	ds_read_b128 v[68:71], v180 offset:288
	ds_read_b128 v[136:139], v180 offset:384
	ds_read_b128 v[52:55], v180 offset:416
	ds_read_b128 v[72:75], v180 offset:320
	ds_read_b128 v[76:79], v180 offset:352
	ds_read_b128 v[56:59], v180 offset:448
	ds_read_b128 v[60:63], v180 offset:480
	s_waitcnt lgkmcnt(14)
	v_mfma_f32_32x32x16_bf16 v[16:31], v[124:127], v[144:147], v[16:31]
	v_exp_f32_e32 v80, v80
	v_exp_f32_e32 v81, v81
	v_exp_f32_e32 v82, v82
	v_exp_f32_e32 v83, v83
	s_waitcnt lgkmcnt(7)
	v_pk_add_f32 v[64:65], v[48:49], v[204:205] op_sel_hi:[1,0] neg_lo:[0,1] neg_hi:[0,1]
	v_pk_add_f32 v[66:67], v[50:51], v[204:205] op_sel_hi:[1,0] neg_lo:[0,1] neg_hi:[0,1]
	s_waitcnt lgkmcnt(2)
	v_mfma_f32_32x32x16_bf16 v[0:15], v[124:127], v[140:143], v[0:15]
	v_exp_f32_e32 v84, v84
	v_exp_f32_e32 v85, v85
	v_exp_f32_e32 v86, v86
	v_exp_f32_e32 v87, v87
	v_pk_add_f32 v[68:69], v[68:69], v[204:205] op_sel_hi:[1,0] neg_lo:[0,1] neg_hi:[0,1]
	v_pk_add_f32 v[70:71], v[70:71], v[204:205] op_sel_hi:[1,0] neg_lo:[0,1] neg_hi:[0,1]
	v_add_u32_e32 v124, s22, v220
	ds_read_b128 v[156:159], v124
	ds_read_b128 v[152:155], v124 offset:512
	v_mfma_f32_32x32x16_bf16 v[16:31], v[120:123], v[132:135], v[16:31]
	v_exp_f32_e32 v88, v88
	v_exp_f32_e32 v89, v89
	v_exp_f32_e32 v90, v90
	v_exp_f32_e32 v91, v91
	v_pk_add_f32 v[72:73], v[72:73], v[204:205] op_sel_hi:[1,0] neg_lo:[0,1] neg_hi:[0,1]
	v_pk_add_f32 v[74:75], v[74:75], v[204:205] op_sel_hi:[1,0] neg_lo:[0,1] neg_hi:[0,1]
	ds_read_b128 v[148:151], v124 offset:2048
	ds_read_b128 v[144:147], v124 offset:2560
	v_mfma_f32_32x32x16_bf16 v[0:15], v[120:123], v[128:131], v[0:15]
	v_exp_f32_e32 v92, v92
	v_exp_f32_e32 v93, v93
	v_exp_f32_e32 v94, v94
	v_exp_f32_e32 v95, v95
	v_pk_add_f32 v[76:77], v[76:77], v[204:205] op_sel_hi:[1,0] neg_lo:[0,1] neg_hi:[0,1]
	v_pk_add_f32 v[78:79], v[78:79], v[204:205] op_sel_hi:[1,0] neg_lo:[0,1] neg_hi:[0,1]
	ds_read_b128 v[140:143], v124 offset:4096
	ds_read_b128 v[132:135], v124 offset:4608
	v_mfma_f32_32x32x16_bf16 v[16:31], v[112:115], v[172:175], v[16:31]
	v_exp_f32_e32 v32, v32
	v_exp_f32_e32 v33, v33
	v_exp_f32_e32 v34, v34
	v_exp_f32_e32 v35, v35
	v_pk_add_f32 v[48:49], v[136:137], v[204:205] op_sel_hi:[1,0] neg_lo:[0,1] neg_hi:[0,1]
	v_pk_add_f32 v[50:51], v[138:139], v[204:205] op_sel_hi:[1,0] neg_lo:[0,1] neg_hi:[0,1]
	s_waitcnt lgkmcnt(6)
	ds_read_b128 v[136:139], v124 offset:6144
	ds_read_b128 v[128:131], v124 offset:6656
	v_mfma_f32_32x32x16_bf16 v[0:15], v[112:115], v[168:171], v[0:15]
	v_exp_f32_e32 v36, v36
	v_exp_f32_e32 v37, v37
	v_exp_f32_e32 v38, v38
	v_exp_f32_e32 v39, v39
	v_pk_add_f32 v[52:53], v[52:53], v[204:205] op_sel_hi:[1,0] neg_lo:[0,1] neg_hi:[0,1]
	v_pk_add_f32 v[54:55], v[54:55], v[204:205] op_sel_hi:[1,0] neg_lo:[0,1] neg_hi:[0,1]
	v_mfma_f32_32x32x16_bf16 v[16:31], v[104:107], v[164:167], v[16:31]
	v_exp_f32_e32 v40, v40
	v_exp_f32_e32 v41, v41
	v_exp_f32_e32 v42, v42
	v_exp_f32_e32 v43, v43
	v_pk_add_f32 v[56:57], v[56:57], v[204:205] op_sel_hi:[1,0] neg_lo:[0,1] neg_hi:[0,1]
	v_pk_add_f32 v[58:59], v[58:59], v[204:205] op_sel_hi:[1,0] neg_lo:[0,1] neg_hi:[0,1]
	v_mfma_f32_32x32x16_bf16 v[0:15], v[104:107], v[160:163], v[0:15]
	v_exp_f32_e32 v44, v44
	v_exp_f32_e32 v45, v45
	v_exp_f32_e32 v46, v46
	v_exp_f32_e32 v47, v47
	v_pk_add_f32 v[60:61], v[60:61], v[204:205] op_sel_hi:[1,0] neg_lo:[0,1] neg_hi:[0,1]
	v_pk_add_f32 v[62:63], v[62:63], v[204:205] op_sel_hi:[1,0] neg_lo:[0,1] neg_hi:[0,1]
	s_add_i32 s100, s22, 0x2000
	s_cmpk_lg_i32 s22, 0x4000
	s_cselect_b32 s24, s100, 0
	s_add_i32 s100, s36, 2
	v_add_u32_e32 v180, 0x200, v180
	v_lshl_add_u64 v[176:177], v[176:177], 0, s[88:89]
	s_cmp_ge_i32 s100, s20
	v_lshl_add_u64 v[178:179], v[178:179], 0, s[88:89]
	s_cselect_b32 s101, 1, 0
	s_waitcnt vmcnt(2) lgkmcnt(0)
	s_barrier
	s_andn2_b64 vcc, exec, s[6:7]
	s_cbranch_vccnz .LBB0_154
	s_waitcnt lgkmcnt(0)
	ds_read_b128 v[160:163], v216 offset:49248
	ds_read_b128 v[164:167], v216 offset:49216
	ds_read_b128 v[168:171], v216 offset:49184
	ds_read_b128 v[172:175], v216 offset:49152
	s_waitcnt lgkmcnt(3)
	v_pk_mul_f32 v[30:31], v[30:31], v[162:163]
	s_waitcnt lgkmcnt(2)
	v_pk_mul_f32 v[26:27], v[26:27], v[166:167]
	s_waitcnt lgkmcnt(1)
	v_pk_mul_f32 v[22:23], v[22:23], v[170:171]
	s_waitcnt lgkmcnt(0)
	v_pk_mul_f32 v[18:19], v[18:19], v[174:175]
	v_pk_mul_f32 v[28:29], v[28:29], v[160:161]
	v_pk_mul_f32 v[24:25], v[24:25], v[164:165]
	v_pk_mul_f32 v[20:21], v[20:21], v[168:169]
	v_pk_mul_f32 v[16:17], v[16:17], v[172:173]
	v_pk_mul_f32 v[14:15], v[14:15], v[162:163]
	v_pk_mul_f32 v[10:11], v[10:11], v[166:167]
	v_pk_mul_f32 v[6:7], v[6:7], v[170:171]
	v_pk_mul_f32 v[2:3], v[2:3], v[174:175]
	v_pk_mul_f32 v[12:13], v[12:13], v[160:161]
	v_pk_mul_f32 v[8:9], v[8:9], v[164:165]
	v_pk_mul_f32 v[4:5], v[4:5], v[168:169]
	v_pk_mul_f32 v[0:1], v[0:1], v[172:173]
.LBB0_154:
	s_mov_b32 s6, s100
	s_cmp_lg_u32 s101, 0
	s_cbranch_scc1 .LBB0_172
	s_mov_b32 s36, s6
	s_mov_b32 s6, s28
	s_mov_b32 s41, s22
	s_mov_b32 s28, s24
	s_branch .LBB0_148
